# DPP butterfly steps in the rowwise reductions combined with the nt stream hints
# speedup vs baseline: 1.0002x; 1.0002x over previous
; DI float lo2f(unsigned v) { return __uint_as_float(v << 16); }
; DI float hi2f(unsigned v) { return __uint_as_float(v & 0xffff0000u); }
; DI float wave_sum(float v) { for (int o = 32; o > 0; o >>= 1) v += __shfl_xor(v, o); return v; }
; DI const float* modvec(PP p, int l, int s, int idx) { return (const float*)(p->ws + S_MOD) + ((size_t)(l * 5 + s) * 6 + idx) * DM; }
; DI void phase_rowwise(PP p, bool first, const u16* src, const float* g_post, int l_res, int gate_idx,
;                       bool write_h, const float* g_pre, int l_mod, int shift_idx, int scale_idx, bool skip_ctx) {
;     ...
;     int b = r / TT, t = r - b * TT;
;     if (skip_ctx && t < CTX) continue;
;     int s = t < CTX ? 4 : b;
;     const float* xin = xrow_in(p, r, first);
;     float x[16];
; #pragma unroll
;     for (int i = 0; i < 4; ++i) { F4 v = *(const F4*)(xin + i * 256 + lane * 4); x[4 * i] = v.x; x[4 * i + 1] = v.y; x[4 * i + 2] = v.z; x[4 * i + 3] = v.w; }
;     if (src) {
;       float y[16]; float ss = 0.f;
; #pragma unroll
;       for (int i = 0; i < 4; ++i) { U2 v = *(const U2*)(src + (size_t)r * DM + i * 256 + lane * 4);
;         y[4 * i] = lo2f(v.x); y[4 * i + 1] = hi2f(v.x); y[4 * i + 2] = lo2f(v.y); y[4 * i + 3] = hi2f(v.y); }
; #pragma unroll
;       for (int i = 0; i < 16; ++i) ss += y[i] * y[i];
;       ss = wave_sum(ss);
;       float rstd = rsqrtf(ss * (1.f / DM) + EPS);
;       const float* gate = modvec(p, l_res, s, gate_idx);
;       float* xo = xrow_out(p, r);
; #pragma unroll
;       for (int i = 0; i < 4; ++i) {
;         int k = i * 256 + lane * 4;
;         F4 g = *(const F4*)(g_post + k); F4 gt = *(const F4*)(gate + k);
;         x[4 * i] += gt.x * (y[4 * i] * rstd * g.x); x[4 * i + 1] += gt.y * (y[4 * i + 1] * rstd * g.y);
;         x[4 * i + 2] += gt.z * (y[4 * i + 2] * rstd * g.z); x[4 * i + 3] += gt.w * (y[4 * i + 3] * rstd * g.w);
;         *(F4*)(xo + k) = mkf4(x[4 * i], x[4 * i + 1], x[4 * i + 2], x[4 * i + 3]);
;       }
.Lrw20_nxt_go:
	s_lshl_b32 s7, s2, 8
	s_add_i32 s7, s7, s3
	s_lshl_b32 s12, s2, 13
	s_add_i32 s12, s12, s3
	s_add_i32 s12, s12, 0xffffff00
	s_cmp_eq_u32 s6, 1
	s_cselect_b32 s7, s7, s12
	s_cselect_b32 s9, 4, s2
	s_cselect_b64 s[12:13], -1, 0
	s_lshl_b32 s7, s7, 12
	v_add_u32_e32 v74, s7, v2
	v_cndmask_b32_e64 v0, v234, v236, s[12:13]
	v_cndmask_b32_e64 v227, v235, v237, s[12:13]
	v_mov_b32_e32 v190, v0
	v_mov_b32_e32 v191, v227
	v_lshl_add_u64 v[190:191], v[190:191], 0, v[74:75]
	v_cndmask_b32_e64 v192, v230, v232, s[12:13]
	v_cndmask_b32_e64 v193, v231, v233, s[12:13]
	v_lshl_add_u64 v[192:193], v[192:193], 0, v[74:75]
	s_lshl_b32 s7, s1, 11
	v_mov_b32_e32 v74, s7
	v_lshl_add_u64 v[196:197], v[180:181], 0, v[74:75]
	global_load_dwordx4 v[26:29], v[190:191], off nt
	global_load_dwordx4 v[30:33], v[190:191], off offset:1024 nt
	global_load_dwordx4 v[34:37], v[190:191], off offset:2048 nt
	global_load_dwordx4 v[38:41], v[190:191], off offset:3072 nt
	global_load_dwordx2 v[42:43], v[196:197], off nt
	global_load_dwordx2 v[44:45], v[196:197], off offset:512 nt
	global_load_dwordx2 v[46:47], v[196:197], off offset:1024 nt
	global_load_dwordx2 v[48:49], v[196:197], off offset:1536 nt
	v_lshlrev_b32_e32 v58, 16, v50
	v_and_b32_e32 v59, 0xffff0000, v50
	v_lshlrev_b32_e32 v60, 16, v51
	v_and_b32_e32 v61, 0xffff0000, v51
	v_lshlrev_b32_e32 v62, 16, v52
	v_and_b32_e32 v63, 0xffff0000, v52
	v_lshlrev_b32_e32 v64, 16, v53
	v_and_b32_e32 v65, 0xffff0000, v53
	v_lshlrev_b32_e32 v66, 16, v54
	v_and_b32_e32 v67, 0xffff0000, v54
	v_lshlrev_b32_e32 v68, 16, v55
	v_and_b32_e32 v69, 0xffff0000, v55
	v_lshlrev_b32_e32 v70, 16, v56
	v_and_b32_e32 v71, 0xffff0000, v56
	v_lshlrev_b32_e32 v72, 16, v57
	v_and_b32_e32 v73, 0xffff0000, v57
	v_mul_f32_e32 v226, v58, v58
	v_mul_f32_e32 v227, v59, v59
	v_add_f32_e32 v226, v226, v227
	v_mul_f32_e32 v227, v60, v60
	v_add_f32_e32 v226, v227, v226
	v_mul_f32_e32 v227, v61, v61
	v_add_f32_e32 v226, v227, v226
	v_mul_f32_e32 v227, v62, v62
	v_add_f32_e32 v226, v227, v226
	v_mul_f32_e32 v227, v63, v63
	v_add_f32_e32 v226, v227, v226
	v_mul_f32_e32 v227, v64, v64
	v_add_f32_e32 v226, v227, v226
	v_mul_f32_e32 v227, v65, v65
	v_add_f32_e32 v226, v227, v226
	v_mul_f32_e32 v227, v66, v66
	v_add_f32_e32 v226, v227, v226
	v_mul_f32_e32 v227, v67, v67
	v_add_f32_e32 v226, v227, v226
	v_mul_f32_e32 v227, v68, v68
	v_add_f32_e32 v226, v227, v226
	v_mul_f32_e32 v227, v69, v69
	v_add_f32_e32 v226, v227, v226
	v_mul_f32_e32 v227, v70, v70
	v_add_f32_e32 v226, v227, v226
	v_mul_f32_e32 v227, v71, v71
	v_add_f32_e32 v226, v227, v226
	v_mul_f32_e32 v227, v72, v72
	v_add_f32_e32 v226, v227, v226
	v_mul_f32_e32 v227, v73, v73
	v_add_f32_e32 v226, v227, v226
	ds_bpermute_b32 v227, v4, v226
	s_waitcnt lgkmcnt(0)
	v_add_f32_e32 v226, v226, v227
	ds_bpermute_b32 v227, v5, v226
	s_waitcnt lgkmcnt(0)
	v_add_f32_e32 v226, v226, v227
	s_nop 1
	v_add_f32_dpp v226, v226, v226 row_ror:8 row_mask:0xf bank_mask:0xf
	ds_bpermute_b32 v227, v7, v226
	s_waitcnt lgkmcnt(0)
	v_add_f32_e32 v226, v226, v227
	s_nop 1
	v_add_f32_dpp v226, v226, v226 quad_perm:[2,3,0,1] row_mask:0xf bank_mask:0xf
	s_nop 1
	v_add_f32_dpp v226, v226, v226 quad_perm:[1,0,3,2] row_mask:0xf bank_mask:0xf
	v_fmamk_f32 v226, v226, 0x3a800000, v162
	s_mov_b32 s7, 0x800000
	v_cmp_gt_f32_e32 vcc, s7, v226
	v_mul_f32_e32 v227, 0x4b800000, v226
	s_nop 0
	v_cndmask_b32_e32 v226, v226, v227, vcc
	v_rsq_f32_e32 v226, v226
	s_nop 0
	v_mul_f32_e32 v227, 0x45800000, v226
	v_cndmask_b32_e32 v228, v226, v227, vcc
	s_waitcnt vmcnt(8)
	v_pk_mul_f32 v[58:59], v[228:229], v[58:59] op_sel_hi:[0,1]
	v_pk_mul_f32 v[58:59], v[58:59], v[118:119]
	v_pk_fma_f32 v[10:11], v[134:135], v[58:59], v[10:11]
	v_pk_mul_f32 v[60:61], v[228:229], v[60:61] op_sel_hi:[0,1]
	v_pk_mul_f32 v[60:61], v[60:61], v[120:121]
	v_pk_fma_f32 v[12:13], v[136:137], v[60:61], v[12:13]
	v_pk_mul_f32 v[62:63], v[228:229], v[62:63] op_sel_hi:[0,1]
	v_pk_mul_f32 v[62:63], v[62:63], v[122:123]
	v_pk_fma_f32 v[14:15], v[138:139], v[62:63], v[14:15]
	v_pk_mul_f32 v[64:65], v[228:229], v[64:65] op_sel_hi:[0,1]
	v_pk_mul_f32 v[64:65], v[64:65], v[124:125]
	v_pk_fma_f32 v[16:17], v[140:141], v[64:65], v[16:17]
	v_pk_mul_f32 v[66:67], v[228:229], v[66:67] op_sel_hi:[0,1]
	v_pk_mul_f32 v[66:67], v[66:67], v[126:127]
	v_pk_fma_f32 v[18:19], v[142:143], v[66:67], v[18:19]
	v_pk_mul_f32 v[68:69], v[228:229], v[68:69] op_sel_hi:[0,1]
	v_pk_mul_f32 v[68:69], v[68:69], v[128:129]
	v_pk_fma_f32 v[20:21], v[144:145], v[68:69], v[20:21]
	v_pk_mul_f32 v[70:71], v[228:229], v[70:71] op_sel_hi:[0,1]
	v_pk_mul_f32 v[70:71], v[70:71], v[130:131]
	v_pk_fma_f32 v[22:23], v[146:147], v[70:71], v[22:23]
	v_pk_mul_f32 v[72:73], v[228:229], v[72:73] op_sel_hi:[0,1]
	v_pk_mul_f32 v[72:73], v[72:73], v[132:133]
	v_pk_fma_f32 v[24:25], v[148:149], v[72:73], v[24:25]
	s_cmp_eq_u32 s10, 1
	s_cbranch_scc1 .Lrw20_noh_st
; DI unsigned pack2(float a, float b) { F2 v = {a, b}; B2 r = __builtin_convertvector(v, B2); return __builtin_bit_cast(unsigned, r); }
; DI float wave_sum(float v) { for (int o = 32; o > 0; o >>= 1) v += __shfl_xor(v, o); return v; }
; DI const float* modvec(PP p, int l, int s, int idx) { return (const float*)(p->ws + S_MOD) + ((size_t)(l * 5 + s) * 6 + idx) * DM; }
; DI void phase_rowwise(PP p, bool first, const u16* src, const float* g_post, int l_res, int gate_idx,
;                       bool write_h, const float* g_pre, int l_mod, int shift_idx, int scale_idx, bool skip_ctx) {
;     ...
;         *(F4*)(xo + k) = mkf4(x[4 * i], x[4 * i + 1], x[4 * i + 2], x[4 * i + 3]);
;       }
;     }
;     if (write_h) {
;       float ss = 0.f;
; #pragma unroll
;       for (int i = 0; i < 16; ++i) ss += x[i] * x[i];
;       ss = wave_sum(ss);
;       float rstd = rsqrtf(ss * (1.f / DM) + EPS);
;       const float* sh = modvec(p, l_mod, s, shift_idx); const float* sc = modvec(p, l_mod, s, scale_idx);
; #pragma unroll
;       for (int i = 0; i < 4; ++i) {
;         int k = i * 256 + lane * 4;
;         F4 g = *(const F4*)(g_pre + k); F4 a = *(const F4*)(sh + k); F4 c = *(const F4*)(sc + k);
;         float h0 = x[4 * i] * rstd * g.x * (1.f + c.x) + a.x, h1 = x[4 * i + 1] * rstd * g.y * (1.f + c.y) + a.y;
;         float h2 = x[4 * i + 2] * rstd * g.z * (1.f + c.z) + a.z, h3 = x[4 * i + 3] * rstd * g.w * (1.f + c.w) + a.w;
;         *(U2*)(H + (size_t)r * DM + k) = mku2(pack2(h0, h1), pack2(h2, h3));
;       }
	global_load_dwordx4 v[118:121], v[172:173], off
	global_load_dwordx4 v[122:125], v[172:173], off offset:1024
	global_load_dwordx4 v[126:129], v[172:173], off offset:2048
	global_load_dwordx4 v[130:133], v[172:173], off offset:3072
	global_load_dwordx4 v[134:137], v[222:223], off
	global_load_dwordx4 v[138:141], v[222:223], off offset:1024
	global_load_dwordx4 v[142:145], v[222:223], off offset:2048
	global_load_dwordx4 v[146:149], v[222:223], off offset:3072
	global_load_dwordx4 v[150:153], v[224:225], off
	global_load_dwordx4 v[154:157], v[224:225], off offset:1024
	global_load_dwordx4 v[158:161], v[224:225], off offset:2048
	global_load_dwordx4 v[166:169], v[224:225], off offset:3072
	global_store_dwordx4 v[188:189], v[10:13], off nt
	global_store_dwordx4 v[188:189], v[14:17], off offset:1024 nt
	global_store_dwordx4 v[188:189], v[18:21], off offset:2048 nt
	global_store_dwordx4 v[188:189], v[22:25], off offset:3072 nt
	v_mul_f32_e32 v226, v10, v10
	v_mul_f32_e32 v227, v11, v11
	v_add_f32_e32 v226, v226, v227
	v_mul_f32_e32 v227, v12, v12
	v_add_f32_e32 v226, v227, v226
	v_mul_f32_e32 v227, v13, v13
	v_add_f32_e32 v226, v227, v226
	v_mul_f32_e32 v227, v14, v14
	v_add_f32_e32 v226, v227, v226
	v_mul_f32_e32 v227, v15, v15
	v_add_f32_e32 v226, v227, v226
	v_mul_f32_e32 v227, v16, v16
	v_add_f32_e32 v226, v227, v226
	v_mul_f32_e32 v227, v17, v17
	v_add_f32_e32 v226, v227, v226
	v_mul_f32_e32 v227, v18, v18
	v_add_f32_e32 v226, v227, v226
	v_mul_f32_e32 v227, v19, v19
	v_add_f32_e32 v226, v227, v226
	v_mul_f32_e32 v227, v20, v20
	v_add_f32_e32 v226, v227, v226
	v_mul_f32_e32 v227, v21, v21
	v_add_f32_e32 v226, v227, v226
	v_mul_f32_e32 v227, v22, v22
	v_add_f32_e32 v226, v227, v226
	v_mul_f32_e32 v227, v23, v23
	v_add_f32_e32 v226, v227, v226
	v_mul_f32_e32 v227, v24, v24
	v_add_f32_e32 v226, v227, v226
	v_mul_f32_e32 v227, v25, v25
	v_add_f32_e32 v226, v227, v226
	ds_bpermute_b32 v227, v4, v226
	s_waitcnt lgkmcnt(0)
	v_add_f32_e32 v226, v226, v227
	ds_bpermute_b32 v227, v5, v226
	s_waitcnt lgkmcnt(0)
	v_add_f32_e32 v226, v226, v227
	s_nop 1
	v_add_f32_dpp v226, v226, v226 row_ror:8 row_mask:0xf bank_mask:0xf
	ds_bpermute_b32 v227, v7, v226
	s_waitcnt lgkmcnt(0)
	v_add_f32_e32 v226, v226, v227
	s_nop 1
	v_add_f32_dpp v226, v226, v226 quad_perm:[2,3,0,1] row_mask:0xf bank_mask:0xf
	s_nop 1
	v_add_f32_dpp v226, v226, v226 quad_perm:[1,0,3,2] row_mask:0xf bank_mask:0xf
	v_fmamk_f32 v226, v226, 0x3a800000, v162
	s_mov_b32 s7, 0x800000
	v_cmp_gt_f32_e32 vcc, s7, v226
	v_mul_f32_e32 v227, 0x4b800000, v226
	s_nop 0
	v_cndmask_b32_e32 v226, v226, v227, vcc
	v_rsq_f32_e32 v226, v226
	s_nop 0
	v_mul_f32_e32 v227, 0x45800000, v226
	v_cndmask_b32_e32 v228, v226, v227, vcc
	s_waitcnt vmcnt(4)
	v_pk_mul_f32 v[10:11], v[10:11], v[228:229] op_sel_hi:[1,0]
	v_pk_mul_f32 v[10:11], v[118:119], v[10:11]
	v_pk_add_f32 v[58:59], v[150:151], 1.0 op_sel_hi:[1,0]
	s_nop 0
	v_pk_fma_f32 v[10:11], v[58:59], v[10:11], v[134:135]
	v_pk_mul_f32 v[12:13], v[12:13], v[228:229] op_sel_hi:[1,0]
	v_pk_mul_f32 v[12:13], v[120:121], v[12:13]
	v_pk_add_f32 v[60:61], v[152:153], 1.0 op_sel_hi:[1,0]
	s_nop 0
	v_pk_fma_f32 v[12:13], v[60:61], v[12:13], v[136:137]
	v_cvt_pk_bf16_f32 v66, v10, v11
	v_cvt_pk_bf16_f32 v67, v12, v13
	global_store_dwordx2 v[218:219], v[66:67], off
	s_nop 1
	v_pk_mul_f32 v[14:15], v[14:15], v[228:229] op_sel_hi:[1,0]
	v_pk_mul_f32 v[14:15], v[122:123], v[14:15]
	v_pk_add_f32 v[58:59], v[154:155], 1.0 op_sel_hi:[1,0]
	s_nop 0
	v_pk_fma_f32 v[14:15], v[58:59], v[14:15], v[138:139]
	v_pk_mul_f32 v[16:17], v[16:17], v[228:229] op_sel_hi:[1,0]
	v_pk_mul_f32 v[16:17], v[124:125], v[16:17]
	v_pk_add_f32 v[60:61], v[156:157], 1.0 op_sel_hi:[1,0]
	s_nop 0
	v_pk_fma_f32 v[16:17], v[60:61], v[16:17], v[140:141]
	v_cvt_pk_bf16_f32 v66, v14, v15
	v_cvt_pk_bf16_f32 v67, v16, v17
	global_store_dwordx2 v[218:219], v[66:67], off offset:512
	s_nop 1
	v_pk_mul_f32 v[18:19], v[18:19], v[228:229] op_sel_hi:[1,0]
	v_pk_mul_f32 v[18:19], v[126:127], v[18:19]
	v_pk_add_f32 v[58:59], v[158:159], 1.0 op_sel_hi:[1,0]
	s_nop 0
	v_pk_fma_f32 v[18:19], v[58:59], v[18:19], v[142:143]
	v_pk_mul_f32 v[20:21], v[20:21], v[228:229] op_sel_hi:[1,0]
	v_pk_mul_f32 v[20:21], v[128:129], v[20:21]
	v_pk_add_f32 v[60:61], v[160:161], 1.0 op_sel_hi:[1,0]
	s_nop 0
	v_pk_fma_f32 v[20:21], v[60:61], v[20:21], v[144:145]
	v_cvt_pk_bf16_f32 v66, v18, v19
	v_cvt_pk_bf16_f32 v67, v20, v21
	global_store_dwordx2 v[218:219], v[66:67], off offset:1024
	s_nop 1
	v_pk_mul_f32 v[22:23], v[22:23], v[228:229] op_sel_hi:[1,0]
	v_pk_mul_f32 v[22:23], v[130:131], v[22:23]
	v_pk_add_f32 v[58:59], v[166:167], 1.0 op_sel_hi:[1,0]
	s_nop 0
	v_pk_fma_f32 v[22:23], v[58:59], v[22:23], v[146:147]
	v_pk_mul_f32 v[24:25], v[24:25], v[228:229] op_sel_hi:[1,0]
	v_pk_mul_f32 v[24:25], v[132:133], v[24:25]
	v_pk_add_f32 v[60:61], v[168:169], 1.0 op_sel_hi:[1,0]
	s_nop 0
	v_pk_fma_f32 v[24:25], v[60:61], v[24:25], v[148:149]
	v_cvt_pk_bf16_f32 v66, v22, v23
	v_cvt_pk_bf16_f32 v67, v24, v25
	global_store_dwordx2 v[218:219], v[66:67], off offset:1536
	s_nop 1
	s_branch .Lrw20_noh

; DI float lo2f(unsigned v) { return __uint_as_float(v << 16); }
; DI float hi2f(unsigned v) { return __uint_as_float(v & 0xffff0000u); }
; DI float wave_sum(float v) { for (int o = 32; o > 0; o >>= 1) v += __shfl_xor(v, o); return v; }
; DI void phase_rowwise(PP p, bool first, const u16* src, const float* g_post, int l_res, int gate_idx,
;                       bool write_h, const float* g_pre, int l_mod, int shift_idx, int scale_idx, bool skip_ctx) {
;     ...
;     int b = r / TT, t = r - b * TT;
;     if (skip_ctx && t < CTX) continue;
;     int s = t < CTX ? 4 : b;
;     const float* xin = xrow_in(p, r, first);
;     float x[16];
; #pragma unroll
;     for (int i = 0; i < 4; ++i) { F4 v = *(const F4*)(xin + i * 256 + lane * 4); x[4 * i] = v.x; x[4 * i + 1] = v.y; x[4 * i + 2] = v.z; x[4 * i + 3] = v.w; }
;     if (src) {
;       float y[16]; float ss = 0.f;
; #pragma unroll
;       for (int i = 0; i < 4; ++i) { U2 v = *(const U2*)(src + (size_t)r * DM + i * 256 + lane * 4);
;         y[4 * i] = lo2f(v.x); y[4 * i + 1] = hi2f(v.x); y[4 * i + 2] = lo2f(v.y); y[4 * i + 3] = hi2f(v.y); }
; #pragma unroll
;       for (int i = 0; i < 16; ++i) ss += y[i] * y[i];
;       ss = wave_sum(ss);
;       float rstd = rsqrtf(ss * (1.f / DM) + EPS);
.Lrw17_nxt_go:
	s_lshl_b32 s7, s2, 8
	s_add_i32 s7, s7, s3
	s_lshl_b32 s12, s2, 13
	s_add_i32 s12, s12, s3
	s_add_i32 s12, s12, 0xffffff00
	s_cmp_eq_u32 s6, 1
	s_cselect_b32 s7, s7, s12
	s_cselect_b32 s9, 4, s2
	s_cselect_b64 s[12:13], -1, 0
	s_lshl_b32 s7, s7, 12
	v_add_u32_e32 v74, s7, v2
	v_cndmask_b32_e64 v0, v234, v236, s[12:13]
	v_cndmask_b32_e64 v227, v235, v237, s[12:13]
	v_mov_b32_e32 v190, v0
	v_mov_b32_e32 v191, v227
	v_lshl_add_u64 v[190:191], v[190:191], 0, v[74:75]
	v_cndmask_b32_e64 v192, v230, v232, s[12:13]
	v_cndmask_b32_e64 v193, v231, v233, s[12:13]
	v_lshl_add_u64 v[192:193], v[192:193], 0, v[74:75]
	s_lshl_b32 s7, s1, 11
	v_mov_b32_e32 v74, s7
	v_lshl_add_u64 v[196:197], v[180:181], 0, v[74:75]
	global_load_dwordx4 v[26:29], v[190:191], off nt
	global_load_dwordx4 v[30:33], v[190:191], off offset:1024 nt
	global_load_dwordx4 v[34:37], v[190:191], off offset:2048 nt
	global_load_dwordx4 v[38:41], v[190:191], off offset:3072 nt
	global_load_dwordx2 v[42:43], v[196:197], off nt
	global_load_dwordx2 v[44:45], v[196:197], off offset:512 nt
	global_load_dwordx2 v[46:47], v[196:197], off offset:1024 nt
	global_load_dwordx2 v[48:49], v[196:197], off offset:1536 nt
	v_lshlrev_b32_e32 v58, 16, v50
	v_and_b32_e32 v59, 0xffff0000, v50
	v_lshlrev_b32_e32 v60, 16, v51
	v_and_b32_e32 v61, 0xffff0000, v51
	v_lshlrev_b32_e32 v62, 16, v52
	v_and_b32_e32 v63, 0xffff0000, v52
	v_lshlrev_b32_e32 v64, 16, v53
	v_and_b32_e32 v65, 0xffff0000, v53
	v_lshlrev_b32_e32 v66, 16, v54
	v_and_b32_e32 v67, 0xffff0000, v54
	v_lshlrev_b32_e32 v68, 16, v55
	v_and_b32_e32 v69, 0xffff0000, v55
	v_lshlrev_b32_e32 v70, 16, v56
	v_and_b32_e32 v71, 0xffff0000, v56
	v_lshlrev_b32_e32 v72, 16, v57
	v_and_b32_e32 v73, 0xffff0000, v57
	v_mul_f32_e32 v226, v58, v58
	v_mul_f32_e32 v227, v59, v59
	v_add_f32_e32 v226, v226, v227
	v_mul_f32_e32 v227, v60, v60
	v_add_f32_e32 v226, v227, v226
	v_mul_f32_e32 v227, v61, v61
	v_add_f32_e32 v226, v227, v226
	v_mul_f32_e32 v227, v62, v62
	v_add_f32_e32 v226, v227, v226
	v_mul_f32_e32 v227, v63, v63
	v_add_f32_e32 v226, v227, v226
	v_mul_f32_e32 v227, v64, v64
	v_add_f32_e32 v226, v227, v226
	v_mul_f32_e32 v227, v65, v65
	v_add_f32_e32 v226, v227, v226
	v_mul_f32_e32 v227, v66, v66
	v_add_f32_e32 v226, v227, v226
	v_mul_f32_e32 v227, v67, v67
	v_add_f32_e32 v226, v227, v226
	v_mul_f32_e32 v227, v68, v68
	v_add_f32_e32 v226, v227, v226
	v_mul_f32_e32 v227, v69, v69
	v_add_f32_e32 v226, v227, v226
	v_mul_f32_e32 v227, v70, v70
	v_add_f32_e32 v226, v227, v226
	v_mul_f32_e32 v227, v71, v71
	v_add_f32_e32 v226, v227, v226
	v_mul_f32_e32 v227, v72, v72
	v_add_f32_e32 v226, v227, v226
	v_mul_f32_e32 v227, v73, v73
	v_add_f32_e32 v226, v227, v226
	ds_bpermute_b32 v227, v4, v226
	s_waitcnt lgkmcnt(0)
	v_add_f32_e32 v226, v226, v227
	ds_bpermute_b32 v227, v5, v226
	s_waitcnt lgkmcnt(0)
	v_add_f32_e32 v226, v226, v227
	s_nop 1
	v_add_f32_dpp v226, v226, v226 row_ror:8 row_mask:0xf bank_mask:0xf
	ds_bpermute_b32 v227, v7, v226
	s_waitcnt lgkmcnt(0)
	v_add_f32_e32 v226, v226, v227
	s_nop 1
	v_add_f32_dpp v226, v226, v226 quad_perm:[2,3,0,1] row_mask:0xf bank_mask:0xf
	s_nop 1
	v_add_f32_dpp v226, v226, v226 quad_perm:[1,0,3,2] row_mask:0xf bank_mask:0xf
	v_fmamk_f32 v226, v226, 0x3a800000, v162
	s_mov_b32 s7, 0x800000
	v_cmp_gt_f32_e32 vcc, s7, v226
	v_mul_f32_e32 v227, 0x4b800000, v226
	s_nop 0
	v_cndmask_b32_e32 v226, v226, v227, vcc
	v_rsq_f32_e32 v226, v226
	s_nop 0
	v_mul_f32_e32 v227, 0x45800000, v226
	v_cndmask_b32_e32 v228, v226, v227, vcc
	s_waitcnt vmcnt(8)
; DI unsigned pack2(float a, float b) { F2 v = {a, b}; B2 r = __builtin_convertvector(v, B2); return __builtin_bit_cast(unsigned, r); }
; DI float wave_sum(float v) { for (int o = 32; o > 0; o >>= 1) v += __shfl_xor(v, o); return v; }
; DI const float* modvec(PP p, int l, int s, int idx) { return (const float*)(p->ws + S_MOD) + ((size_t)(l * 5 + s) * 6 + idx) * DM; }
; DI void phase_rowwise(PP p, bool first, const u16* src, const float* g_post, int l_res, int gate_idx,
;                       bool write_h, const float* g_pre, int l_mod, int shift_idx, int scale_idx, bool skip_ctx) {
;     ...
; #pragma unroll
;       for (int i = 0; i < 4; ++i) {
;         int k = i * 256 + lane * 4;
;         F4 g = *(const F4*)(g_post + k); F4 gt = *(const F4*)(gate + k);
;         x[4 * i] += gt.x * (y[4 * i] * rstd * g.x); x[4 * i + 1] += gt.y * (y[4 * i + 1] * rstd * g.y);
;         x[4 * i + 2] += gt.z * (y[4 * i + 2] * rstd * g.z); x[4 * i + 3] += gt.w * (y[4 * i + 3] * rstd * g.w);
;         *(F4*)(xo + k) = mkf4(x[4 * i], x[4 * i + 1], x[4 * i + 2], x[4 * i + 3]);
;       }
;     }
;     if (write_h) {
;       float ss = 0.f;
; #pragma unroll
;       for (int i = 0; i < 16; ++i) ss += x[i] * x[i];
;       ss = wave_sum(ss);
;       float rstd = rsqrtf(ss * (1.f / DM) + EPS);
;       const float* sh = modvec(p, l_mod, s, shift_idx); const float* sc = modvec(p, l_mod, s, scale_idx);
; #pragma unroll
;       for (int i = 0; i < 4; ++i) {
;         int k = i * 256 + lane * 4;
;         F4 g = *(const F4*)(g_pre + k); F4 a = *(const F4*)(sh + k); F4 c = *(const F4*)(sc + k);
;         float h0 = x[4 * i] * rstd * g.x * (1.f + c.x) + a.x, h1 = x[4 * i + 1] * rstd * g.y * (1.f + c.y) + a.y;
;         float h2 = x[4 * i + 2] * rstd * g.z * (1.f + c.z) + a.z, h3 = x[4 * i + 3] * rstd * g.w * (1.f + c.w) + a.w;
;         *(U2*)(H + (size_t)r * DM + k) = mku2(pack2(h0, h1), pack2(h2, h3));
;       }
	v_pk_mul_f32 v[58:59], v[228:229], v[58:59] op_sel_hi:[0,1]
	v_pk_mul_f32 v[58:59], v[58:59], v[118:119]
	v_pk_fma_f32 v[10:11], v[134:135], v[58:59], v[10:11]
	v_pk_mul_f32 v[60:61], v[228:229], v[60:61] op_sel_hi:[0,1]
	v_pk_mul_f32 v[60:61], v[60:61], v[120:121]
	v_pk_fma_f32 v[12:13], v[136:137], v[60:61], v[12:13]
	v_pk_mul_f32 v[62:63], v[228:229], v[62:63] op_sel_hi:[0,1]
	v_pk_mul_f32 v[62:63], v[62:63], v[122:123]
	v_pk_fma_f32 v[14:15], v[138:139], v[62:63], v[14:15]
	v_pk_mul_f32 v[64:65], v[228:229], v[64:65] op_sel_hi:[0,1]
	v_pk_mul_f32 v[64:65], v[64:65], v[124:125]
	v_pk_fma_f32 v[16:17], v[140:141], v[64:65], v[16:17]
	v_pk_mul_f32 v[66:67], v[228:229], v[66:67] op_sel_hi:[0,1]
	v_pk_mul_f32 v[66:67], v[66:67], v[126:127]
	v_pk_fma_f32 v[18:19], v[142:143], v[66:67], v[18:19]
	v_pk_mul_f32 v[68:69], v[228:229], v[68:69] op_sel_hi:[0,1]
	v_pk_mul_f32 v[68:69], v[68:69], v[128:129]
	v_pk_fma_f32 v[20:21], v[144:145], v[68:69], v[20:21]
	v_pk_mul_f32 v[70:71], v[228:229], v[70:71] op_sel_hi:[0,1]
	v_pk_mul_f32 v[70:71], v[70:71], v[130:131]
	v_pk_fma_f32 v[22:23], v[146:147], v[70:71], v[22:23]
	v_pk_mul_f32 v[72:73], v[228:229], v[72:73] op_sel_hi:[0,1]
	v_pk_mul_f32 v[72:73], v[72:73], v[132:133]
	v_pk_fma_f32 v[24:25], v[148:149], v[72:73], v[24:25]
	global_load_dwordx4 v[118:121], v[172:173], off
	global_load_dwordx4 v[122:125], v[172:173], off offset:1024
	global_load_dwordx4 v[126:129], v[172:173], off offset:2048
	global_load_dwordx4 v[130:133], v[172:173], off offset:3072
	global_load_dwordx4 v[134:137], v[222:223], off
	global_load_dwordx4 v[138:141], v[222:223], off offset:1024
	global_load_dwordx4 v[142:145], v[222:223], off offset:2048
	global_load_dwordx4 v[146:149], v[222:223], off offset:3072
	global_load_dwordx4 v[150:153], v[224:225], off
	global_load_dwordx4 v[154:157], v[224:225], off offset:1024
	global_load_dwordx4 v[158:161], v[224:225], off offset:2048
	global_load_dwordx4 v[166:169], v[224:225], off offset:3072
	global_store_dwordx4 v[188:189], v[10:13], off nt
	global_store_dwordx4 v[188:189], v[14:17], off offset:1024 nt
	global_store_dwordx4 v[188:189], v[18:21], off offset:2048 nt
	global_store_dwordx4 v[188:189], v[22:25], off offset:3072 nt
	v_mul_f32_e32 v226, v10, v10
	v_mul_f32_e32 v227, v11, v11
	v_add_f32_e32 v226, v226, v227
	v_mul_f32_e32 v227, v12, v12
	v_add_f32_e32 v226, v227, v226
	v_mul_f32_e32 v227, v13, v13
	v_add_f32_e32 v226, v227, v226
	v_mul_f32_e32 v227, v14, v14
	v_add_f32_e32 v226, v227, v226
	v_mul_f32_e32 v227, v15, v15
	v_add_f32_e32 v226, v227, v226
	v_mul_f32_e32 v227, v16, v16
	v_add_f32_e32 v226, v227, v226
	v_mul_f32_e32 v227, v17, v17
	v_add_f32_e32 v226, v227, v226
	v_mul_f32_e32 v227, v18, v18
	v_add_f32_e32 v226, v227, v226
	v_mul_f32_e32 v227, v19, v19
	v_add_f32_e32 v226, v227, v226
	v_mul_f32_e32 v227, v20, v20
	v_add_f32_e32 v226, v227, v226
	v_mul_f32_e32 v227, v21, v21
	v_add_f32_e32 v226, v227, v226
	v_mul_f32_e32 v227, v22, v22
	v_add_f32_e32 v226, v227, v226
	v_mul_f32_e32 v227, v23, v23
	v_add_f32_e32 v226, v227, v226
	v_mul_f32_e32 v227, v24, v24
	v_add_f32_e32 v226, v227, v226
	v_mul_f32_e32 v227, v25, v25
	v_add_f32_e32 v226, v227, v226
	ds_bpermute_b32 v227, v4, v226
	s_waitcnt lgkmcnt(0)
	v_add_f32_e32 v226, v226, v227
	ds_bpermute_b32 v227, v5, v226
	s_waitcnt lgkmcnt(0)
	v_add_f32_e32 v226, v226, v227
	s_nop 1
	v_add_f32_dpp v226, v226, v226 row_ror:8 row_mask:0xf bank_mask:0xf
	ds_bpermute_b32 v227, v7, v226
	s_waitcnt lgkmcnt(0)
	v_add_f32_e32 v226, v226, v227
	s_nop 1
	v_add_f32_dpp v226, v226, v226 quad_perm:[2,3,0,1] row_mask:0xf bank_mask:0xf
	s_nop 1
	v_add_f32_dpp v226, v226, v226 quad_perm:[1,0,3,2] row_mask:0xf bank_mask:0xf
	v_fmamk_f32 v226, v226, 0x3a800000, v162
	s_mov_b32 s7, 0x800000
	v_cmp_gt_f32_e32 vcc, s7, v226
	v_mul_f32_e32 v227, 0x4b800000, v226
	s_nop 0
	v_cndmask_b32_e32 v226, v226, v227, vcc
	v_rsq_f32_e32 v226, v226
	s_nop 0
	v_mul_f32_e32 v227, 0x45800000, v226
	v_cndmask_b32_e32 v228, v226, v227, vcc
	s_waitcnt vmcnt(4)
	v_pk_mul_f32 v[10:11], v[10:11], v[228:229] op_sel_hi:[1,0]
	v_pk_mul_f32 v[10:11], v[118:119], v[10:11]
	v_pk_add_f32 v[58:59], v[150:151], 1.0 op_sel_hi:[1,0]
	s_nop 0
	v_pk_fma_f32 v[10:11], v[58:59], v[10:11], v[134:135]
	v_pk_mul_f32 v[12:13], v[12:13], v[228:229] op_sel_hi:[1,0]
	v_pk_mul_f32 v[12:13], v[120:121], v[12:13]
	v_pk_add_f32 v[60:61], v[152:153], 1.0 op_sel_hi:[1,0]
	s_nop 0
	v_pk_fma_f32 v[12:13], v[60:61], v[12:13], v[136:137]
	v_cvt_pk_bf16_f32 v66, v10, v11
	v_cvt_pk_bf16_f32 v67, v12, v13
	global_store_dwordx2 v[218:219], v[66:67], off
	s_nop 1
	v_pk_mul_f32 v[14:15], v[14:15], v[228:229] op_sel_hi:[1,0]
	v_pk_mul_f32 v[14:15], v[122:123], v[14:15]
	v_pk_add_f32 v[58:59], v[154:155], 1.0 op_sel_hi:[1,0]
	s_nop 0
	v_pk_fma_f32 v[14:15], v[58:59], v[14:15], v[138:139]
	v_pk_mul_f32 v[16:17], v[16:17], v[228:229] op_sel_hi:[1,0]
	v_pk_mul_f32 v[16:17], v[124:125], v[16:17]
	v_pk_add_f32 v[60:61], v[156:157], 1.0 op_sel_hi:[1,0]
	s_nop 0
	v_pk_fma_f32 v[16:17], v[60:61], v[16:17], v[140:141]
	v_cvt_pk_bf16_f32 v66, v14, v15
	v_cvt_pk_bf16_f32 v67, v16, v17
	global_store_dwordx2 v[218:219], v[66:67], off offset:512
	s_nop 1
	v_pk_mul_f32 v[18:19], v[18:19], v[228:229] op_sel_hi:[1,0]
	v_pk_mul_f32 v[18:19], v[126:127], v[18:19]
	v_pk_add_f32 v[58:59], v[158:159], 1.0 op_sel_hi:[1,0]
	s_nop 0
	v_pk_fma_f32 v[18:19], v[58:59], v[18:19], v[142:143]
	v_pk_mul_f32 v[20:21], v[20:21], v[228:229] op_sel_hi:[1,0]
	v_pk_mul_f32 v[20:21], v[128:129], v[20:21]
	v_pk_add_f32 v[60:61], v[160:161], 1.0 op_sel_hi:[1,0]
	s_nop 0
	v_pk_fma_f32 v[20:21], v[60:61], v[20:21], v[144:145]
	v_cvt_pk_bf16_f32 v66, v18, v19
	v_cvt_pk_bf16_f32 v67, v20, v21
	global_store_dwordx2 v[218:219], v[66:67], off offset:1024
	s_nop 1
	v_pk_mul_f32 v[22:23], v[22:23], v[228:229] op_sel_hi:[1,0]
	v_pk_mul_f32 v[22:23], v[130:131], v[22:23]
	v_pk_add_f32 v[58:59], v[166:167], 1.0 op_sel_hi:[1,0]
	s_nop 0
	v_pk_fma_f32 v[22:23], v[58:59], v[22:23], v[146:147]
	v_pk_mul_f32 v[24:25], v[24:25], v[228:229] op_sel_hi:[1,0]
	v_pk_mul_f32 v[24:25], v[132:133], v[24:25]
	v_pk_add_f32 v[60:61], v[168:169], 1.0 op_sel_hi:[1,0]
	s_nop 0
	v_pk_fma_f32 v[24:25], v[60:61], v[24:25], v[148:149]
	v_cvt_pk_bf16_f32 v66, v22, v23
	v_cvt_pk_bf16_f32 v67, v24, v25
	global_store_dwordx2 v[218:219], v[66:67], off offset:1536
	s_nop 1
	s_branch .Lrw17_noh

; DI void phase_rowwise(PP p, bool first, const u16* src, const float* g_post, int l_res, int gate_idx,
;                       bool write_h, const float* g_pre, int l_mod, int shift_idx, int scale_idx, bool skip_ctx) {
;     ...
;   for (int r = get_bid() * 4 + w; r < ROWS; r += gridDim.x * 4) {
;     int b = r / TT, t = r - b * TT;
;     if (skip_ctx && t < CTX) continue;
;     int s = t < CTX ? 4 : b;
;     const float* xin = xrow_in(p, r, first);
;     float x[16];
; #pragma unroll
;     for (int i = 0; i < 4; ++i) { F4 v = *(const F4*)(xin + i * 256 + lane * 4); x[4 * i] = v.x; x[4 * i + 1] = v.y; x[4 * i + 2] = v.z; x[4 * i + 3] = v.w; }
;     if (src) {
;       float y[16]; float ss = 0.f;
; #pragma unroll
;       for (int i = 0; i < 4; ++i) { U2 v = *(const U2*)(src + (size_t)r * DM + i * 256 + lane * 4);
;         y[4 * i] = lo2f(v.x); y[4 * i + 1] = hi2f(v.x); y[4 * i + 2] = lo2f(v.y); y[4 * i + 3] = hi2f(v.y); }
; #pragma unroll
;       for (int i = 0; i < 16; ++i) ss += y[i] * y[i];
;       ss = wave_sum(ss);
;       float rstd = rsqrtf(ss * (1.f / DM) + EPS);
;       const float* gate = modvec(p, l_res, s, gate_idx);
;       float* xo = xrow_out(p, r);
; #pragma unroll
;       for (int i = 0; i < 4; ++i) {
;         int k = i * 256 + lane * 4;
;         F4 g = *(const F4*)(g_post + k); F4 gt = *(const F4*)(gate + k);
;         x[4 * i] += gt.x * (y[4 * i] * rstd * g.x); x[4 * i + 1] += gt.y * (y[4 * i + 1] * rstd * g.y);
;         x[4 * i + 2] += gt.z * (y[4 * i + 2] * rstd * g.z); x[4 * i + 3] += gt.w * (y[4 * i + 3] * rstd * g.w);
;         *(F4*)(xo + k) = mkf4(x[4 * i], x[4 * i + 1], x[4 * i + 2], x[4 * i + 3]);
;       }
;     }
;     if (write_h) {
;       float ss = 0.f;
; #pragma unroll
;       for (int i = 0; i < 16; ++i) ss += x[i] * x[i];
;       ss = wave_sum(ss);
;       float rstd = rsqrtf(ss * (1.f / DM) + EPS);
;       const float* sh = modvec(p, l_mod, s, shift_idx); const float* sc = modvec(p, l_mod, s, scale_idx);
; #pragma unroll
;       for (int i = 0; i < 4; ++i) {
;         int k = i * 256 + lane * 4;
;         F4 g = *(const F4*)(g_pre + k); F4 a = *(const F4*)(sh + k); F4 c = *(const F4*)(sc + k);
;         float h0 = x[4 * i] * rstd * g.x * (1.f + c.x) + a.x, h1 = x[4 * i + 1] * rstd * g.y * (1.f + c.y) + a.y;
;         float h2 = x[4 * i + 2] * rstd * g.z * (1.f + c.z) + a.z, h3 = x[4 * i + 3] * rstd * g.w * (1.f + c.w) + a.w;
.Lrw2_loop:
	v_mov_b32_e32 v10, v26
	v_mov_b32_e32 v11, v27
	v_mov_b32_e32 v12, v28
	v_mov_b32_e32 v13, v29
	v_mov_b32_e32 v14, v30
	v_mov_b32_e32 v15, v31
	v_mov_b32_e32 v16, v32
	v_mov_b32_e32 v17, v33
	v_mov_b32_e32 v18, v34
	v_mov_b32_e32 v19, v35
	v_mov_b32_e32 v20, v36
	v_mov_b32_e32 v21, v37
	v_mov_b32_e32 v22, v38
	v_mov_b32_e32 v23, v39
	v_mov_b32_e32 v24, v40
	v_mov_b32_e32 v25, v41
	s_mov_b32 s4, s5
	s_mul_i32 s7, s4, 0x6000
	v_mov_b32_e32 v42, s7
	v_lshl_add_u64 v[222:223], v[176:177], 0, v[42:43]
	v_lshl_add_u64 v[224:225], v[178:179], 0, v[42:43]
	s_lshl_b32 s7, s0, 11
	v_mov_b32_e32 v42, s7
	v_lshl_add_u64 v[218:219], v[182:183], 0, v[42:43]
	global_load_dwordx4 v[118:121], v[172:173], off
	global_load_dwordx4 v[122:125], v[172:173], off offset:1024
	global_load_dwordx4 v[126:129], v[172:173], off offset:2048
	global_load_dwordx4 v[130:133], v[172:173], off offset:3072
	global_load_dwordx4 v[134:137], v[222:223], off
	global_load_dwordx4 v[138:141], v[222:223], off offset:1024
	global_load_dwordx4 v[142:145], v[222:223], off offset:2048
	global_load_dwordx4 v[146:149], v[222:223], off offset:3072
	global_load_dwordx4 v[150:153], v[224:225], off
	global_load_dwordx4 v[154:157], v[224:225], off offset:1024
	global_load_dwordx4 v[158:161], v[224:225], off offset:2048
	global_load_dwordx4 v[166:169], v[224:225], off offset:3072
	s_add_i32 s1, s0, s90
	s_mov_b32 s8, 0
	s_cmp_ge_u32 s1, 0x8400
	s_cselect_b32 s8, 1, 0
	s_cselect_b32 s1, s0, s1
	s_cmp_ge_u32 s1, 0x2100
	s_cselect_b32 s2, 1, 0
	s_cmp_ge_u32 s1, 0x4200
	s_addc_u32 s2, s2, 0
	s_cmp_ge_u32 s1, 0x6300
	s_addc_u32 s2, s2, 0
	s_mul_i32 s3, s2, 0x2100
	s_sub_i32 s3, s1, s3
	s_lshl_b32 s7, s2, 8
	s_add_i32 s7, s7, s3
	s_lshl_b32 s9, s2, 13
	s_add_i32 s9, s9, s3
	s_add_i32 s9, s9, 0xffffff00
	s_cmp_lt_u32 s3, 0x100
	s_cselect_b32 s7, s7, s9
	s_cselect_b32 s5, 4, s2
	s_cselect_b64 s[12:13], -1, 0
	s_lshl_b32 s7, s7, 12
	v_add_u32_e32 v42, s7, v2
	v_cndmask_b32_e64 v190, v234, v236, s[12:13]
	v_cndmask_b32_e64 v191, v235, v237, s[12:13]
	v_lshl_add_u64 v[190:191], v[190:191], 0, v[42:43]
	global_load_dwordx4 v[26:29], v[190:191], off nt
	global_load_dwordx4 v[30:33], v[190:191], off offset:1024 nt
	global_load_dwordx4 v[34:37], v[190:191], off offset:2048 nt
	global_load_dwordx4 v[38:41], v[190:191], off offset:3072 nt
	v_mul_f32_e32 v226, v11, v11
	v_fmac_f32_e32 v226, v10, v10
	v_fmac_f32_e32 v226, v12, v12
	v_fmac_f32_e32 v226, v13, v13
	v_fmac_f32_e32 v226, v14, v14
	v_fmac_f32_e32 v226, v15, v15
	v_fmac_f32_e32 v226, v16, v16
	v_fmac_f32_e32 v226, v17, v17
	v_fmac_f32_e32 v226, v18, v18
	v_fmac_f32_e32 v226, v19, v19
	v_fmac_f32_e32 v226, v20, v20
	v_fmac_f32_e32 v226, v21, v21
	v_mul_f32_e32 v227, v22, v22
	v_add_f32_e32 v226, v227, v226
	v_mul_f32_e32 v227, v23, v23
	v_add_f32_e32 v226, v227, v226
	v_mul_f32_e32 v227, v24, v24
	v_add_f32_e32 v226, v227, v226
	v_mul_f32_e32 v227, v25, v25
	v_add_f32_e32 v226, v227, v226
	ds_bpermute_b32 v227, v4, v226
	s_waitcnt lgkmcnt(0)
	v_add_f32_e32 v226, v226, v227
	ds_bpermute_b32 v227, v5, v226
	s_waitcnt lgkmcnt(0)
	v_add_f32_e32 v226, v226, v227
	s_nop 1
	v_add_f32_dpp v226, v226, v226 row_ror:8 row_mask:0xf bank_mask:0xf
	ds_bpermute_b32 v227, v7, v226
	s_waitcnt lgkmcnt(0)
	v_add_f32_e32 v226, v226, v227
	s_nop 1
	v_add_f32_dpp v226, v226, v226 quad_perm:[2,3,0,1] row_mask:0xf bank_mask:0xf
	s_nop 1
	v_add_f32_dpp v226, v226, v226 quad_perm:[1,0,3,2] row_mask:0xf bank_mask:0xf
	v_fmamk_f32 v226, v226, 0x3a800000, v162
	s_mov_b32 s7, 0x800000
	v_cmp_gt_f32_e32 vcc, s7, v226
	v_mul_f32_e32 v227, 0x4b800000, v226
	s_nop 0
	v_cndmask_b32_e32 v226, v226, v227, vcc
	v_rsq_f32_e32 v226, v226
	s_nop 0
	v_mul_f32_e32 v227, 0x45800000, v226
	v_cndmask_b32_e32 v228, v226, v227, vcc
	s_waitcnt vmcnt(4)
	v_pk_mul_f32 v[10:11], v[10:11], v[228:229] op_sel_hi:[1,0]
	v_pk_mul_f32 v[10:11], v[118:119], v[10:11]
	v_pk_add_f32 v[44:45], v[150:151], 1.0 op_sel_hi:[1,0]
	s_nop 0
	v_pk_fma_f32 v[10:11], v[44:45], v[10:11], v[134:135]
	v_pk_mul_f32 v[12:13], v[12:13], v[228:229] op_sel_hi:[1,0]
	v_pk_mul_f32 v[12:13], v[120:121], v[12:13]
	v_pk_add_f32 v[46:47], v[152:153], 1.0 op_sel_hi:[1,0]
	s_nop 0
	v_pk_fma_f32 v[12:13], v[46:47], v[12:13], v[136:137]
	v_cvt_pk_bf16_f32 v48, v10, v11
	v_cvt_pk_bf16_f32 v49, v12, v13
	global_store_dwordx2 v[218:219], v[48:49], off
	s_nop 1
	v_pk_mul_f32 v[14:15], v[14:15], v[228:229] op_sel_hi:[1,0]
	v_pk_mul_f32 v[14:15], v[122:123], v[14:15]
	v_pk_add_f32 v[44:45], v[154:155], 1.0 op_sel_hi:[1,0]
	s_nop 0
	v_pk_fma_f32 v[14:15], v[44:45], v[14:15], v[138:139]
	v_pk_mul_f32 v[16:17], v[16:17], v[228:229] op_sel_hi:[1,0]
	v_pk_mul_f32 v[16:17], v[124:125], v[16:17]
	v_pk_add_f32 v[46:47], v[156:157], 1.0 op_sel_hi:[1,0]
	s_nop 0
	v_pk_fma_f32 v[16:17], v[46:47], v[16:17], v[140:141]
	v_cvt_pk_bf16_f32 v48, v14, v15
	v_cvt_pk_bf16_f32 v49, v16, v17
	global_store_dwordx2 v[218:219], v[48:49], off offset:512
	s_nop 1
	v_pk_mul_f32 v[18:19], v[18:19], v[228:229] op_sel_hi:[1,0]
	v_pk_mul_f32 v[18:19], v[126:127], v[18:19]
	v_pk_add_f32 v[44:45], v[158:159], 1.0 op_sel_hi:[1,0]
	s_nop 0
	v_pk_fma_f32 v[18:19], v[44:45], v[18:19], v[142:143]
	v_pk_mul_f32 v[20:21], v[20:21], v[228:229] op_sel_hi:[1,0]
	v_pk_mul_f32 v[20:21], v[128:129], v[20:21]
	v_pk_add_f32 v[46:47], v[160:161], 1.0 op_sel_hi:[1,0]
	s_nop 0
	v_pk_fma_f32 v[20:21], v[46:47], v[20:21], v[144:145]
	v_cvt_pk_bf16_f32 v48, v18, v19
	v_cvt_pk_bf16_f32 v49, v20, v21
	global_store_dwordx2 v[218:219], v[48:49], off offset:1024
	s_nop 1
	v_pk_mul_f32 v[22:23], v[22:23], v[228:229] op_sel_hi:[1,0]
	v_pk_mul_f32 v[22:23], v[130:131], v[22:23]
	v_pk_add_f32 v[44:45], v[166:167], 1.0 op_sel_hi:[1,0]
	s_nop 0
	v_pk_fma_f32 v[22:23], v[44:45], v[22:23], v[146:147]
	v_pk_mul_f32 v[24:25], v[24:25], v[228:229] op_sel_hi:[1,0]
	v_pk_mul_f32 v[24:25], v[132:133], v[24:25]
	v_pk_add_f32 v[46:47], v[168:169], 1.0 op_sel_hi:[1,0]
	s_nop 0
	v_pk_fma_f32 v[24:25], v[46:47], v[24:25], v[148:149]
	v_cvt_pk_bf16_f32 v48, v22, v23
	v_cvt_pk_bf16_f32 v49, v24, v25
	global_store_dwordx2 v[218:219], v[48:49], off offset:1536
	s_nop 1
	s_waitcnt vmcnt(4)
	s_cmp_eq_u32 s8, 1
	s_cbranch_scc1 .Lrw2_done
	s_mov_b32 s0, s1
	s_branch .Lrw2_loop
